# flat hand-written converter in prologue; last 4096 items of the L0 down weight segment converted by the 64 idle workgroups of the gate|up L0 step's last round instead of in the prologue
# speedup vs baseline: 1.0002x; 1.0002x over previous
; __device__ __forceinline__ void convert_segments(const Args& args, unsigned char* ws, LAS unsigned char* lds, int seg_lo, int seg_hi, int part_lo, int part_hi, int nparts, int wid, int nw, int wave, int lane) {
;     ...
;     for (int sI = seg_lo; sI < seg_hi; ++sI) {
;         const Seg sg = seg_at(sI);
;         const int nblk = sg.ncols / 64, nit = (sg.K / 64) * nblk;
;         const float* W = args.in[sg.in_idx] + (size_t)sg.src_l * sg.K * sg.N;
;         bf16* WT = (bf16*)(ws + WS_W + (size_t)sg.layer * LAYER_W + (size_t)sg.wsub_mib * MiB);
;         const int it_lo = (int)((long)nit * part_lo / nparts), it_hi = (int)((long)nit * part_hi / nparts);
cvp_nx1:
	s_cmp_lt_u32 s50, s23
	s_cbranch_scc1 cvp_nf1
	s_sub_i32 s50, s50, s23
	s_mov_b32 s23, 0
	s_add_i32 s70, s70, 1
	s_cmp_ge_i32 s70, s61
	s_cbranch_scc1 cvp_done
	s_mul_i32 s4, s70, 40
	s_getpc_b64 s[6:7]
	s_add_u32 s6, s6, __const._Z6seg_ati.segs@rel32@lo+4
	s_addc_u32 s7, s7, __const._Z6seg_ati.segs@rel32@hi+12
	s_add_u32 s6, s6, s4
	s_addc_u32 s7, s7, 0
	s_load_dwordx8 s[8:15], s[6:7], 0x0
	s_load_dwordx2 s[18:19], s[6:7], 0x20
	s_waitcnt lgkmcnt(0)
	s_lshr_b32 s20, s13, 6
	s_lshr_b32 s21, s11, 6
	s_mul_i32 s22, s20, s21
	s_lshl_b32 s4, s8, 3
	s_load_dwordx2 s[24:25], s[0:1], s4
	s_mul_i32 s5, s11, s10
	s_mul_i32 s5, s5, s9
	s_lshl_b32 s5, s5, 2
	s_lshl_b32 s6, s12, 2
	s_add_u32 s5, s5, s6
	s_waitcnt lgkmcnt(0)
	s_add_u32 s24, s24, s5
	s_addc_u32 s25, s25, 0
	s_mul_i32 s5, s14, 0x1a400000
	s_lshl_b32 s6, s15, 20
	s_add_u32 s5, s5, s6
	s_add_u32 s5, s5, 0x2d400000
	s_add_u32 s26, s68, s5
	s_addc_u32 s27, s69, 0
	s_mov_b32 s41, 0
	s_mov_b32 s23, s22
	s_sub_i32 s4, s22, 4096
	s_cmp_eq_u32 s70, 15
	s_cselect_b32 s4, s4, s22
	s_cmpk_eq_i32 s88, 0x100
	s_cselect_b32 s23, s4, s22
	v_mul_lo_u32 v168, v161, s10
	v_add_u32_e32 v168, v168, v162
	v_lshlrev_b32_e32 v168, 2, v168
	s_lshl_b32 s48, s10, 4
	s_branch cvp_nx1

; __device__ __forceinline__ void convert_segments(const Args& args, unsigned char* ws, LAS unsigned char* lds, int seg_lo, int seg_hi, int part_lo, int part_hi, int nparts, int wid, int nw, int wave, int lane) {
;     ...
;     for (int sI = seg_lo; sI < seg_hi; ++sI) {
;         const Seg sg = seg_at(sI);
;         const int nblk = sg.ncols / 64, nit = (sg.K / 64) * nblk;
;         const float* W = args.in[sg.in_idx] + (size_t)sg.src_l * sg.K * sg.N;
;         bf16* WT = (bf16*)(ws + WS_W + (size_t)sg.layer * LAYER_W + (size_t)sg.wsub_mib * MiB);
;         const int it_lo = (int)((long)nit * part_lo / nparts), it_hi = (int)((long)nit * part_hi / nparts);
cvp_nx2:
	s_cmp_lt_u32 s50, s23
	s_cbranch_scc1 cvp_nf2
	s_sub_i32 s50, s50, s23
	s_mov_b32 s23, 0
	s_add_i32 s70, s70, 1
	s_cmp_ge_i32 s70, s61
	s_cbranch_scc1 cvp_pre
	s_mul_i32 s4, s70, 40
	s_getpc_b64 s[6:7]
	s_add_u32 s6, s6, __const._Z6seg_ati.segs@rel32@lo+4
	s_addc_u32 s7, s7, __const._Z6seg_ati.segs@rel32@hi+12
	s_add_u32 s6, s6, s4
	s_addc_u32 s7, s7, 0
	s_load_dwordx8 s[8:15], s[6:7], 0x0
	s_load_dwordx2 s[18:19], s[6:7], 0x20
	s_waitcnt lgkmcnt(0)
	s_lshr_b32 s20, s13, 6
	s_lshr_b32 s21, s11, 6
	s_mul_i32 s22, s20, s21
	s_lshl_b32 s4, s8, 3
	s_load_dwordx2 s[24:25], s[0:1], s4
	s_mul_i32 s5, s11, s10
	s_mul_i32 s5, s5, s9
	s_lshl_b32 s5, s5, 2
	s_lshl_b32 s6, s12, 2
	s_add_u32 s5, s5, s6
	s_waitcnt lgkmcnt(0)
	s_add_u32 s24, s24, s5
	s_addc_u32 s25, s25, 0
	s_mul_i32 s5, s14, 0x1a400000
	s_lshl_b32 s6, s15, 20
	s_add_u32 s5, s5, s6
	s_add_u32 s5, s5, 0x2d400000
	s_add_u32 s26, s68, s5
	s_addc_u32 s27, s69, 0
	s_mov_b32 s41, 0
	s_mov_b32 s23, s22
	s_sub_i32 s4, s22, 4096
	s_cmp_eq_u32 s70, 15
	s_cselect_b32 s4, s4, s22
	s_cmpk_eq_i32 s88, 0x100
	s_cselect_b32 s23, s4, s22
	v_mul_lo_u32 v168, v161, s10
	v_add_u32_e32 v168, v168, v162
	v_lshlrev_b32_e32 v168, 2, v168
	s_lshl_b32 s48, s10, 4
	s_branch cvp_nx2

; __device__ __forceinline__ void convert_segments(const Args& args, unsigned char* ws, LAS unsigned char* lds, int seg_lo, int seg_hi, int part_lo, int part_hi, int nparts, int wid, int nw, int wave, int lane) {
;     ...
;     for (int sI = seg_lo; sI < seg_hi; ++sI) {
;         const Seg sg = seg_at(sI);
;         const int nblk = sg.ncols / 64, nit = (sg.K / 64) * nblk;
;         const float* W = args.in[sg.in_idx] + (size_t)sg.src_l * sg.K * sg.N;
;         bf16* WT = (bf16*)(ws + WS_W + (size_t)sg.layer * LAYER_W + (size_t)sg.wsub_mib * MiB);
;         const int it_lo = (int)((long)nit * part_lo / nparts), it_hi = (int)((long)nit * part_hi / nparts);
cvp_nx3:
	s_cmp_lt_u32 s50, s23
	s_cbranch_scc1 cvp_nf3
	s_sub_i32 s50, s50, s23
	s_mov_b32 s23, 0
	s_add_i32 s70, s70, 1
	s_cmp_ge_i32 s70, s61
	s_cbranch_scc1 cvp_nlA
	s_mul_i32 s4, s70, 40
	s_getpc_b64 s[6:7]
	s_add_u32 s6, s6, __const._Z6seg_ati.segs@rel32@lo+4
	s_addc_u32 s7, s7, __const._Z6seg_ati.segs@rel32@hi+12
	s_add_u32 s6, s6, s4
	s_addc_u32 s7, s7, 0
	s_load_dwordx8 s[8:15], s[6:7], 0x0
	s_load_dwordx2 s[18:19], s[6:7], 0x20
	s_waitcnt lgkmcnt(0)
	s_lshr_b32 s20, s13, 6
	s_lshr_b32 s21, s11, 6
	s_mul_i32 s22, s20, s21
	s_lshl_b32 s4, s8, 3
	s_load_dwordx2 s[24:25], s[0:1], s4
	s_mul_i32 s5, s11, s10
	s_mul_i32 s5, s5, s9
	s_lshl_b32 s5, s5, 2
	s_lshl_b32 s6, s12, 2
	s_add_u32 s5, s5, s6
	s_waitcnt lgkmcnt(0)
	s_add_u32 s24, s24, s5
	s_addc_u32 s25, s25, 0
	s_mul_i32 s5, s14, 0x1a400000
	s_lshl_b32 s6, s15, 20
	s_add_u32 s5, s5, s6
	s_add_u32 s5, s5, 0x2d400000
	s_add_u32 s26, s68, s5
	s_addc_u32 s27, s69, 0
	s_mov_b32 s41, 0
	s_mov_b32 s23, s22
	s_sub_i32 s4, s22, 4096
	s_cmp_eq_u32 s70, 15
	s_cselect_b32 s4, s4, s22
	s_cmpk_eq_i32 s88, 0x100
	s_cselect_b32 s23, s4, s22
	v_mul_lo_u32 v168, v161, s10
	v_add_u32_e32 v168, v168, v162
	v_lshlrev_b32_e32 v168, 2, v168
	s_lshl_b32 s48, s10, 4
	s_branch cvp_nx3

; __device__ __forceinline__ void convert_segments(const Args& args, unsigned char* ws, LAS unsigned char* lds, int seg_lo, int seg_hi, int part_lo, int part_hi, int nparts, int wid, int nw, int wave, int lane) {
;     ...
;     for (int sI = seg_lo; sI < seg_hi; ++sI) {
;         const Seg sg = seg_at(sI);
;         const int nblk = sg.ncols / 64, nit = (sg.K / 64) * nblk;
;         const float* W = args.in[sg.in_idx] + (size_t)sg.src_l * sg.K * sg.N;
;         bf16* WT = (bf16*)(ws + WS_W + (size_t)sg.layer * LAYER_W + (size_t)sg.wsub_mib * MiB);
;         const int it_lo = (int)((long)nit * part_lo / nparts), it_hi = (int)((long)nit * part_hi / nparts);
cvp_nx4:
	s_cmp_lt_u32 s50, s23
	s_cbranch_scc1 cvp_nf4
	s_sub_i32 s50, s50, s23
	s_mov_b32 s23, 0
	s_add_i32 s70, s70, 1
	s_cmp_ge_i32 s70, s61
	s_cbranch_scc1 cvp_nlB
	s_mul_i32 s4, s70, 40
	s_getpc_b64 s[6:7]
	s_add_u32 s6, s6, __const._Z6seg_ati.segs@rel32@lo+4
	s_addc_u32 s7, s7, __const._Z6seg_ati.segs@rel32@hi+12
	s_add_u32 s6, s6, s4
	s_addc_u32 s7, s7, 0
	s_load_dwordx8 s[8:15], s[6:7], 0x0
	s_load_dwordx2 s[18:19], s[6:7], 0x20
	s_waitcnt lgkmcnt(0)
	s_lshr_b32 s20, s13, 6
	s_lshr_b32 s21, s11, 6
	s_mul_i32 s22, s20, s21
	s_lshl_b32 s4, s8, 3
	s_load_dwordx2 s[24:25], s[0:1], s4
	s_mul_i32 s5, s11, s10
	s_mul_i32 s5, s5, s9
	s_lshl_b32 s5, s5, 2
	s_lshl_b32 s6, s12, 2
	s_add_u32 s5, s5, s6
	s_waitcnt lgkmcnt(0)
	s_add_u32 s24, s24, s5
	s_addc_u32 s25, s25, 0
	s_mul_i32 s5, s14, 0x1a400000
	s_lshl_b32 s6, s15, 20
	s_add_u32 s5, s5, s6
	s_add_u32 s5, s5, 0x2d400000
	s_add_u32 s26, s68, s5
	s_addc_u32 s27, s69, 0
	s_mov_b32 s41, 0
	s_mov_b32 s23, s22
	s_sub_i32 s4, s22, 4096
	s_cmp_eq_u32 s70, 15
	s_cselect_b32 s4, s4, s22
	s_cmpk_eq_i32 s88, 0x100
	s_cselect_b32 s23, s4, s22
	v_mul_lo_u32 v168, v161, s10
	v_add_u32_e32 v168, v168, v162
	v_lshlrev_b32_e32 v168, 2, v168
	s_lshl_b32 s48, s10, 4
	s_branch cvp_nx4

; __device__ __forceinline__ void tr_load(const float* src, int N, f32x4 (&v)[16], int lane) {
;     const int r4 = lane >> 4, c4 = (lane & 15) * 4;
; #pragma unroll
;     for (int i = 0; i < 16; ++i) v[i] = *(const f32x4*)(src + (size_t)(4 * i + r4) * N + c4);
; __device__ __forceinline__ void convert_segments(const Args& args, unsigned char* ws, LAS unsigned char* lds, int seg_lo, int seg_hi, int part_lo, int part_hi, int nparts, int wid, int nw, int wave, int lane) {
;     ...
;     for (int sI = seg_lo; sI < seg_hi; ++sI) {
;         const Seg sg = seg_at(sI);
;         const int nblk = sg.ncols / 64, nit = (sg.K / 64) * nblk;
;         const float* W = args.in[sg.in_idx] + (size_t)sg.src_l * sg.K * sg.N;
;         bf16* WT = (bf16*)(ws + WS_W + (size_t)sg.layer * LAYER_W + (size_t)sg.wsub_mib * MiB);
;         const int it_lo = (int)((long)nit * part_lo / nparts), it_hi = (int)((long)nit * part_hi / nparts);
;         int it = it_lo + wid;
;         f32x4 v[16];
;         if (it < it_hi) { const int kb = it / nblk, nb = it - kb * nblk; tr_load(W + (size_t)(64 * kb) * sg.N + sg.scol + 64 * nb, sg.N, v, lane); }
; #pragma unroll 1
;         for (; it < it_hi; it += nw) {
;             const int kb = it / nblk, nb = it - kb * nblk;
;             const int drow = sg.ilv ? (256 * (nb >> 1) + 64 * (nb & 1) + sg.drow) : (sg.drow + 64 * nb);
;             tr_to_lds(v, scr, lane);
;             const int itn = it + nw;
;             if (itn < it_hi) { const int kbn = itn / nblk, nbn = itn - kbn * nblk; tr_load(W + (size_t)(64 * kbn) * sg.N + sg.scol + 64 * nbn, sg.N, v, lane); }
.LBB0_1405:
	s_cmpk_lg_i32 s88, 0x100
	s_cbranch_scc1 cvt_done
	s_cmpk_lt_i32 s2, 0xc0
	s_cbranch_scc1 cvt_done
	s_cmp_lt_i32 s36, 12
	s_cbranch_scc0 cvt_done
	s_cmp_gt_i32 s37, 11
	s_cbranch_scc0 cvt_done
	s_lshl_b32 s4, s2, 3
	s_add_i32 s4, s4, s89
	s_add_i32 s50, s4, 0xfffffa00
	s_movk_i32 s63, 0x200
	s_mov_b32 s61, 16
	s_mov_b32 s70, 14
	s_mov_b32 s23, 0
	v_mbcnt_lo_u32_b32 v160, -1, 0
	v_mbcnt_hi_u32_b32 v160, -1, v160
	v_lshrrev_b32_e32 v161, 4, v160
	v_and_b32_e32 v162, 15, v160
	v_lshlrev_b32_e32 v162, 2, v162
	s_mul_i32 s66, s89, 0x4100
	v_mul_u32_u24_e32 v163, 0x41, v161
	v_add_u32_e32 v163, v163, v162
	v_lshl_add_u32 v163, v163, 2, s66
	v_and_b32_e32 v164, 7, v160
	v_lshrrev_b32_e32 v165, 3, v160
	v_mul_u32_u24_e32 v166, 0x208, v164
	v_add_u32_e32 v166, v166, v165
	v_lshl_add_u32 v166, v166, 2, s66
	v_add_u32_e32 v167, 0x410, v166
	s_load_dwordx2 s[68:69], s[0:1], 0xe8
	s_waitcnt lgkmcnt(0)
cvt_nx5:
	s_cmp_lt_u32 s50, s23
	s_cbranch_scc1 cvt_nf5
	s_sub_i32 s50, s50, s23
	s_mov_b32 s23, 0
	s_add_i32 s70, s70, 1
	s_cmp_ge_i32 s70, s61
	s_cbranch_scc1 cvt_done
	s_mul_i32 s4, s70, 40
	s_getpc_b64 s[6:7]
	s_add_u32 s6, s6, __const._Z6seg_ati.segs@rel32@lo+4
	s_addc_u32 s7, s7, __const._Z6seg_ati.segs@rel32@hi+12
	s_add_u32 s6, s6, s4
	s_addc_u32 s7, s7, 0
	s_load_dwordx8 s[8:15], s[6:7], 0x0
	s_load_dwordx2 s[18:19], s[6:7], 0x20
	s_waitcnt lgkmcnt(0)
	s_lshr_b32 s20, s13, 6
	s_lshr_b32 s21, s11, 6
	s_mul_i32 s22, s20, s21
	s_lshl_b32 s4, s8, 3
	s_load_dwordx2 s[24:25], s[0:1], s4
	s_mul_i32 s5, s11, s10
	s_mul_i32 s5, s5, s9
	s_lshl_b32 s5, s5, 2
	s_lshl_b32 s6, s12, 2
	s_add_u32 s5, s5, s6
	s_waitcnt lgkmcnt(0)
	s_add_u32 s24, s24, s5
	s_addc_u32 s25, s25, 0
	s_mul_i32 s5, s14, 0x1a400000
	s_lshl_b32 s6, s15, 20
	s_add_u32 s5, s5, s6
	s_add_u32 s5, s5, 0x2d400000
	s_add_u32 s26, s68, s5
	s_addc_u32 s27, s69, 0
	s_sub_i32 s41, s22, 4096
	s_movk_i32 s23, 4096
	v_mul_lo_u32 v168, v161, s10
	v_add_u32_e32 v168, v168, v162
	v_lshlrev_b32_e32 v168, 2, v168
	s_lshl_b32 s48, s10, 4
	s_branch cvt_nx5
cvt_nf5:
	s_add_i32 s43, s41, s50
	s_add_i32 s50, s50, s63
	v_cvt_f32_u32_e32 v170, s43
	v_cvt_f32_u32_e32 v171, s20
	v_rcp_f32_e32 v171, v171
	s_nop 1
	v_mul_f32_e32 v170, v170, v171
	v_cvt_u32_f32_e32 v170, v170
	s_nop 1
	v_readfirstlane_b32 s46, v170
	s_mul_i32 s72, s46, s20
	s_sub_i32 s47, s43, s72
	s_cmp_lt_i32 s47, 0
	s_cselect_b32 s72, s20, 0
	s_cselect_b32 s73, 1, 0
	s_add_i32 s47, s47, s72
	s_sub_i32 s46, s46, s73
	s_cmp_ge_i32 s47, s20
	s_cselect_b32 s72, s20, 0
	s_cselect_b32 s73, 1, 0
	s_sub_i32 s47, s47, s72
	s_add_i32 s46, s46, s73
	s_cmp_ge_i32 s47, s20
	s_cselect_b32 s72, s20, 0
	s_cselect_b32 s73, 1, 0
	s_sub_i32 s47, s47, s72
	s_add_i32 s46, s46, s73
	s_mul_i32 s4, s46, s10
	s_add_i32 s4, s4, s47
	s_lshl_b32 s4, s4, 8
	s_add_u32 s56, s24, s4
	s_addc_u32 s57, s25, 0
	s_lshr_b32 s4, s47, 1
	s_lshl_b32 s4, s4, 8
	s_and_b32 s5, s47, 1
	s_lshl_b32 s5, s5, 6
	s_add_i32 s4, s4, s5
	s_lshl_b32 s5, s47, 6
	s_cmp_lg_u32 s19, 0
	s_cselect_b32 s4, s4, s5
	s_add_i32 s4, s4, s18
	s_mul_i32 s4, s4, s11
	s_lshl_b32 s5, s46, 6
	s_add_i32 s4, s4, s5
	s_lshl_b32 s4, s4, 1
	s_add_u32 s74, s26, s4
	s_addc_u32 s75, s27, 0
	s_mov_b32 s76, s11
	global_load_dwordx4 v[0:3], v168, s[56:57]
	s_add_u32 s56, s56, s48
	s_addc_u32 s57, s57, 0
	global_load_dwordx4 v[4:7], v168, s[56:57]
	s_add_u32 s56, s56, s48
	s_addc_u32 s57, s57, 0
	global_load_dwordx4 v[8:11], v168, s[56:57]
	s_add_u32 s56, s56, s48
	s_addc_u32 s57, s57, 0
	global_load_dwordx4 v[12:15], v168, s[56:57]
	s_add_u32 s56, s56, s48
	s_addc_u32 s57, s57, 0
	global_load_dwordx4 v[16:19], v168, s[56:57]
	s_add_u32 s56, s56, s48
	s_addc_u32 s57, s57, 0
	global_load_dwordx4 v[20:23], v168, s[56:57]
	s_add_u32 s56, s56, s48
	s_addc_u32 s57, s57, 0
	global_load_dwordx4 v[24:27], v168, s[56:57]
	s_add_u32 s56, s56, s48
	s_addc_u32 s57, s57, 0
	global_load_dwordx4 v[28:31], v168, s[56:57]
	s_add_u32 s56, s56, s48
	s_addc_u32 s57, s57, 0
	global_load_dwordx4 v[32:35], v168, s[56:57]
	s_add_u32 s56, s56, s48
	s_addc_u32 s57, s57, 0
	global_load_dwordx4 v[36:39], v168, s[56:57]
	s_add_u32 s56, s56, s48
	s_addc_u32 s57, s57, 0
	global_load_dwordx4 v[40:43], v168, s[56:57]
	s_add_u32 s56, s56, s48
	s_addc_u32 s57, s57, 0
	global_load_dwordx4 v[44:47], v168, s[56:57]
	s_add_u32 s56, s56, s48
	s_addc_u32 s57, s57, 0
	global_load_dwordx4 v[48:51], v168, s[56:57]
	s_add_u32 s56, s56, s48
	s_addc_u32 s57, s57, 0
	global_load_dwordx4 v[52:55], v168, s[56:57]
	s_add_u32 s56, s56, s48
	s_addc_u32 s57, s57, 0
	global_load_dwordx4 v[56:59], v168, s[56:57]
	s_add_u32 s56, s56, s48
	s_addc_u32 s57, s57, 0
	global_load_dwordx4 v[60:63], v168, s[56:57]
	s_mov_b32 s58, 1
	s_mov_b32 s59, 0
cvt_nx6:
	s_cmp_lt_u32 s50, s23
	s_cbranch_scc1 cvt_nf6
	s_sub_i32 s50, s50, s23
	s_mov_b32 s23, 0
	s_add_i32 s70, s70, 1
	s_cmp_ge_i32 s70, s61
	s_cbranch_scc1 cvt_pre
	s_mul_i32 s4, s70, 40
	s_getpc_b64 s[6:7]
	s_add_u32 s6, s6, __const._Z6seg_ati.segs@rel32@lo+4
	s_addc_u32 s7, s7, __const._Z6seg_ati.segs@rel32@hi+12
	s_add_u32 s6, s6, s4
	s_addc_u32 s7, s7, 0
	s_load_dwordx8 s[8:15], s[6:7], 0x0
	s_load_dwordx2 s[18:19], s[6:7], 0x20
	s_waitcnt lgkmcnt(0)
	s_lshr_b32 s20, s13, 6
	s_lshr_b32 s21, s11, 6
	s_mul_i32 s22, s20, s21
	s_lshl_b32 s4, s8, 3
	s_load_dwordx2 s[24:25], s[0:1], s4
	s_mul_i32 s5, s11, s10
	s_mul_i32 s5, s5, s9
	s_lshl_b32 s5, s5, 2
	s_lshl_b32 s6, s12, 2
	s_add_u32 s5, s5, s6
	s_waitcnt lgkmcnt(0)
	s_add_u32 s24, s24, s5
	s_addc_u32 s25, s25, 0
	s_mul_i32 s5, s14, 0x1a400000
	s_lshl_b32 s6, s15, 20
	s_add_u32 s5, s5, s6
	s_add_u32 s5, s5, 0x2d400000
	s_add_u32 s26, s68, s5
	s_addc_u32 s27, s69, 0
	s_sub_i32 s41, s22, 4096
	s_movk_i32 s23, 4096
	v_mul_lo_u32 v168, v161, s10
	v_add_u32_e32 v168, v168, v162
	v_lshlrev_b32_e32 v168, 2, v168
	s_lshl_b32 s48, s10, 4
	s_branch cvt_nx6
; #define LAS __attribute__((address_space(3)))
; #define LDS_WAIT() asm volatile("s_waitcnt lgkmcnt(0)" ::: "memory")
; __device__ __forceinline__ void tr_load(const float* src, int N, f32x4 (&v)[16], int lane) {
;     const int r4 = lane >> 4, c4 = (lane & 15) * 4;
; #pragma unroll
;     for (int i = 0; i < 16; ++i) v[i] = *(const f32x4*)(src + (size_t)(4 * i + r4) * N + c4);
; __device__ __forceinline__ void tr_to_lds(const f32x4 (&v)[16], LAS float* scr, int lane) {
;     const int r4 = lane >> 4, c4 = (lane & 15) * 4;
; #pragma unroll
;     for (int i = 0; i < 16; ++i) { LAS float* s = scr + (4 * i + r4) * 65 + c4; s[0] = v[i].x; s[1] = v[i].y; s[2] = v[i].z; s[3] = v[i].w; }
;     LDS_WAIT(); asm volatile("" ::: "memory");
; }
cvt_nf6:
	s_add_i32 s43, s41, s50
	s_add_i32 s50, s50, s63
	v_cvt_f32_u32_e32 v170, s43
	v_cvt_f32_u32_e32 v171, s20
	v_rcp_f32_e32 v171, v171
	s_nop 1
	v_mul_f32_e32 v170, v170, v171
	v_cvt_u32_f32_e32 v170, v170
	s_nop 1
	v_readfirstlane_b32 s46, v170
	s_mul_i32 s72, s46, s20
	s_sub_i32 s47, s43, s72
	s_cmp_lt_i32 s47, 0
	s_cselect_b32 s72, s20, 0
	s_cselect_b32 s73, 1, 0
	s_add_i32 s47, s47, s72
	s_sub_i32 s46, s46, s73
	s_cmp_ge_i32 s47, s20
	s_cselect_b32 s72, s20, 0
	s_cselect_b32 s73, 1, 0
	s_sub_i32 s47, s47, s72
	s_add_i32 s46, s46, s73
	s_cmp_ge_i32 s47, s20
	s_cselect_b32 s72, s20, 0
	s_cselect_b32 s73, 1, 0
	s_sub_i32 s47, s47, s72
	s_add_i32 s46, s46, s73
	s_mul_i32 s4, s46, s10
	s_add_i32 s4, s4, s47
	s_lshl_b32 s4, s4, 8
	s_add_u32 s56, s24, s4
	s_addc_u32 s57, s25, 0
	s_lshr_b32 s4, s47, 1
	s_lshl_b32 s4, s4, 8
	s_and_b32 s5, s47, 1
	s_lshl_b32 s5, s5, 6
	s_add_i32 s4, s4, s5
	s_lshl_b32 s5, s47, 6
	s_cmp_lg_u32 s19, 0
	s_cselect_b32 s4, s4, s5
	s_add_i32 s4, s4, s18
	s_mul_i32 s4, s4, s11
	s_lshl_b32 s5, s46, 6
	s_add_i32 s4, s4, s5
	s_lshl_b32 s4, s4, 1
	s_add_u32 s78, s26, s4
	s_addc_u32 s79, s27, 0
	s_mov_b32 s77, s11
	global_load_dwordx4 v[64:67], v168, s[56:57]
	s_add_u32 s56, s56, s48
	s_addc_u32 s57, s57, 0
	global_load_dwordx4 v[68:71], v168, s[56:57]
	s_add_u32 s56, s56, s48
	s_addc_u32 s57, s57, 0
	global_load_dwordx4 v[72:75], v168, s[56:57]
	s_add_u32 s56, s56, s48
	s_addc_u32 s57, s57, 0
	global_load_dwordx4 v[76:79], v168, s[56:57]
	s_add_u32 s56, s56, s48
	s_addc_u32 s57, s57, 0
	global_load_dwordx4 v[80:83], v168, s[56:57]
	s_add_u32 s56, s56, s48
	s_addc_u32 s57, s57, 0
	global_load_dwordx4 v[84:87], v168, s[56:57]
	s_add_u32 s56, s56, s48
	s_addc_u32 s57, s57, 0
	global_load_dwordx4 v[88:91], v168, s[56:57]
	s_add_u32 s56, s56, s48
	s_addc_u32 s57, s57, 0
	global_load_dwordx4 v[92:95], v168, s[56:57]
	s_add_u32 s56, s56, s48
	s_addc_u32 s57, s57, 0
	global_load_dwordx4 v[96:99], v168, s[56:57]
	s_add_u32 s56, s56, s48
	s_addc_u32 s57, s57, 0
	global_load_dwordx4 v[100:103], v168, s[56:57]
	s_add_u32 s56, s56, s48
	s_addc_u32 s57, s57, 0
	global_load_dwordx4 v[104:107], v168, s[56:57]
	s_add_u32 s56, s56, s48
	s_addc_u32 s57, s57, 0
	global_load_dwordx4 v[108:111], v168, s[56:57]
	s_add_u32 s56, s56, s48
	s_addc_u32 s57, s57, 0
	global_load_dwordx4 v[112:115], v168, s[56:57]
	s_add_u32 s56, s56, s48
	s_addc_u32 s57, s57, 0
	global_load_dwordx4 v[116:119], v168, s[56:57]
	s_add_u32 s56, s56, s48
	s_addc_u32 s57, s57, 0
	global_load_dwordx4 v[120:123], v168, s[56:57]
	s_add_u32 s56, s56, s48
	s_addc_u32 s57, s57, 0
	global_load_dwordx4 v[124:127], v168, s[56:57]
	s_mov_b32 s59, 1
cvt_pre:
	s_waitcnt vmcnt(0)
cvt_stepA:
	s_cmp_lg_u32 s59, 0
	s_cbranch_scc0 cvt_w0A
	s_waitcnt vmcnt(32)
	s_branch cvt_goA
cvt_w0A:
	s_waitcnt vmcnt(0)
cvt_goA:
	ds_write_b32 v163, v0 offset:0
	ds_write_b32 v163, v1 offset:4
	ds_write_b32 v163, v2 offset:8
	ds_write_b32 v163, v3 offset:12
	ds_write_b32 v163, v4 offset:1040
	ds_write_b32 v163, v5 offset:1044
	ds_write_b32 v163, v6 offset:1048
	ds_write_b32 v163, v7 offset:1052
	ds_write_b32 v163, v8 offset:2080
	ds_write_b32 v163, v9 offset:2084
	ds_write_b32 v163, v10 offset:2088
	ds_write_b32 v163, v11 offset:2092
	ds_write_b32 v163, v12 offset:3120
	ds_write_b32 v163, v13 offset:3124
	ds_write_b32 v163, v14 offset:3128
	ds_write_b32 v163, v15 offset:3132
	ds_write_b32 v163, v16 offset:4160
	ds_write_b32 v163, v17 offset:4164
	ds_write_b32 v163, v18 offset:4168
	ds_write_b32 v163, v19 offset:4172
	ds_write_b32 v163, v20 offset:5200
	ds_write_b32 v163, v21 offset:5204
	ds_write_b32 v163, v22 offset:5208
	ds_write_b32 v163, v23 offset:5212
	ds_write_b32 v163, v24 offset:6240
	ds_write_b32 v163, v25 offset:6244
	ds_write_b32 v163, v26 offset:6248
	ds_write_b32 v163, v27 offset:6252
	ds_write_b32 v163, v28 offset:7280
	ds_write_b32 v163, v29 offset:7284
	ds_write_b32 v163, v30 offset:7288
	ds_write_b32 v163, v31 offset:7292
	ds_write_b32 v163, v32 offset:8320
	ds_write_b32 v163, v33 offset:8324
	ds_write_b32 v163, v34 offset:8328
	ds_write_b32 v163, v35 offset:8332
	ds_write_b32 v163, v36 offset:9360
	ds_write_b32 v163, v37 offset:9364
	ds_write_b32 v163, v38 offset:9368
	ds_write_b32 v163, v39 offset:9372
	ds_write_b32 v163, v40 offset:10400
	ds_write_b32 v163, v41 offset:10404
	ds_write_b32 v163, v42 offset:10408
	ds_write_b32 v163, v43 offset:10412
	ds_write_b32 v163, v44 offset:11440
	ds_write_b32 v163, v45 offset:11444
	ds_write_b32 v163, v46 offset:11448
	ds_write_b32 v163, v47 offset:11452
	ds_write_b32 v163, v48 offset:12480
	ds_write_b32 v163, v49 offset:12484
	ds_write_b32 v163, v50 offset:12488
	ds_write_b32 v163, v51 offset:12492
	ds_write_b32 v163, v52 offset:13520
	ds_write_b32 v163, v53 offset:13524
	ds_write_b32 v163, v54 offset:13528
	ds_write_b32 v163, v55 offset:13532
	ds_write_b32 v163, v56 offset:14560
	ds_write_b32 v163, v57 offset:14564
	ds_write_b32 v163, v58 offset:14568
	ds_write_b32 v163, v59 offset:14572
	ds_write_b32 v163, v60 offset:15600
	ds_write_b32 v163, v61 offset:15604
	ds_write_b32 v163, v62 offset:15608
	ds_write_b32 v163, v63 offset:15612
	s_waitcnt lgkmcnt(0)
	s_mov_b32 s54, s74
	s_mov_b32 s55, s75
	s_lshl_b32 s49, s76, 4
	v_mul_lo_u32 v169, v165, s76
	v_lshl_add_u32 v169, v164, 3, v169
	v_lshlrev_b32_e32 v169, 1, v169
	s_mov_b32 s58, 0
; #define LAS __attribute__((address_space(3)))
; #define LDS_WAIT() asm volatile("s_waitcnt lgkmcnt(0)" ::: "memory")
; __device__ __forceinline__ unsigned pk2(float lo, float hi) { const f32x2c v = {lo, hi}; return __builtin_bit_cast(unsigned, __builtin_convertvector(v, bf16x2c)); }
; __device__ __forceinline__ void tr_store(bf16* dst, int K, const LAS float* scr, int lane) {
;     const int c = lane & 7;
; #pragma unroll
;     for (int j = 0; j < 8; ++j) { const int n = (lane >> 3) + 8 * j; const LAS float* s = scr + (8 * c) * 65 + n;
;         v4u o; o.x = pk2(s[0], s[65]); o.y = pk2(s[130], s[195]); o.z = pk2(s[260], s[325]); o.w = pk2(s[390], s[455]);
;         *(v4u*)(dst + (size_t)n * K + 8 * c) = o; }
;     LDS_WAIT(); asm volatile("" ::: "memory");
; __device__ __forceinline__ void convert_segments(const Args& args, unsigned char* ws, LAS unsigned char* lds, int seg_lo, int seg_hi, int part_lo, int part_hi, int nparts, int wid, int nw, int wave, int lane) {
;     ...
;         for (; it < it_hi; it += nw) {
;             const int kb = it / nblk, nb = it - kb * nblk;
;             const int drow = sg.ilv ? (256 * (nb >> 1) + 64 * (nb & 1) + sg.drow) : (sg.drow + 64 * nb);
;             tr_to_lds(v, scr, lane);
;             const int itn = it + nw;
;             if (itn < it_hi) { const int kbn = itn / nblk, nbn = itn - kbn * nblk; tr_load(W + (size_t)(64 * kbn) * sg.N + sg.scol + 64 * nbn, sg.N, v, lane); }
;             tr_store(WT + (size_t)drow * sg.K + 64 * kb, sg.K, scr, lane);
cvt_nx7:
	s_cmp_lt_u32 s50, s23
	s_cbranch_scc1 cvt_nf7
	s_sub_i32 s50, s50, s23
	s_mov_b32 s23, 0
	s_add_i32 s70, s70, 1
	s_cmp_ge_i32 s70, s61
	s_cbranch_scc1 cvt_nlA
	s_mul_i32 s4, s70, 40
	s_getpc_b64 s[6:7]
	s_add_u32 s6, s6, __const._Z6seg_ati.segs@rel32@lo+4
	s_addc_u32 s7, s7, __const._Z6seg_ati.segs@rel32@hi+12
	s_add_u32 s6, s6, s4
	s_addc_u32 s7, s7, 0
	s_load_dwordx8 s[8:15], s[6:7], 0x0
	s_load_dwordx2 s[18:19], s[6:7], 0x20
	s_waitcnt lgkmcnt(0)
	s_lshr_b32 s20, s13, 6
	s_lshr_b32 s21, s11, 6
	s_mul_i32 s22, s20, s21
	s_lshl_b32 s4, s8, 3
	s_load_dwordx2 s[24:25], s[0:1], s4
	s_mul_i32 s5, s11, s10
	s_mul_i32 s5, s5, s9
	s_lshl_b32 s5, s5, 2
	s_lshl_b32 s6, s12, 2
	s_add_u32 s5, s5, s6
	s_waitcnt lgkmcnt(0)
	s_add_u32 s24, s24, s5
	s_addc_u32 s25, s25, 0
	s_mul_i32 s5, s14, 0x1a400000
	s_lshl_b32 s6, s15, 20
	s_add_u32 s5, s5, s6
	s_add_u32 s5, s5, 0x2d400000
	s_add_u32 s26, s68, s5
	s_addc_u32 s27, s69, 0
	s_sub_i32 s41, s22, 4096
	s_movk_i32 s23, 4096
	v_mul_lo_u32 v168, v161, s10
	v_add_u32_e32 v168, v168, v162
	v_lshlrev_b32_e32 v168, 2, v168
	s_lshl_b32 s48, s10, 4
	s_branch cvt_nx7
cvt_nf7:
	s_add_i32 s43, s41, s50
	s_add_i32 s50, s50, s63
	v_cvt_f32_u32_e32 v170, s43
	v_cvt_f32_u32_e32 v171, s20
	v_rcp_f32_e32 v171, v171
	s_nop 1
	v_mul_f32_e32 v170, v170, v171
	v_cvt_u32_f32_e32 v170, v170
	s_nop 1
	v_readfirstlane_b32 s46, v170
	s_mul_i32 s72, s46, s20
	s_sub_i32 s47, s43, s72
	s_cmp_lt_i32 s47, 0
	s_cselect_b32 s72, s20, 0
	s_cselect_b32 s73, 1, 0
	s_add_i32 s47, s47, s72
	s_sub_i32 s46, s46, s73
	s_cmp_ge_i32 s47, s20
	s_cselect_b32 s72, s20, 0
	s_cselect_b32 s73, 1, 0
	s_sub_i32 s47, s47, s72
	s_add_i32 s46, s46, s73
	s_cmp_ge_i32 s47, s20
	s_cselect_b32 s72, s20, 0
	s_cselect_b32 s73, 1, 0
	s_sub_i32 s47, s47, s72
	s_add_i32 s46, s46, s73
	s_mul_i32 s4, s46, s10
	s_add_i32 s4, s4, s47
	s_lshl_b32 s4, s4, 8
	s_add_u32 s56, s24, s4
	s_addc_u32 s57, s25, 0
	s_lshr_b32 s4, s47, 1
	s_lshl_b32 s4, s4, 8
	s_and_b32 s5, s47, 1
	s_lshl_b32 s5, s5, 6
	s_add_i32 s4, s4, s5
	s_lshl_b32 s5, s47, 6
	s_cmp_lg_u32 s19, 0
	s_cselect_b32 s4, s4, s5
	s_add_i32 s4, s4, s18
	s_mul_i32 s4, s4, s11
	s_lshl_b32 s5, s46, 6
	s_add_i32 s4, s4, s5
	s_lshl_b32 s4, s4, 1
	s_add_u32 s74, s26, s4
	s_addc_u32 s75, s27, 0
	s_mov_b32 s76, s11
	global_load_dwordx4 v[0:3], v168, s[56:57]
	s_add_u32 s56, s56, s48
	s_addc_u32 s57, s57, 0
	global_load_dwordx4 v[4:7], v168, s[56:57]
	s_add_u32 s56, s56, s48
	s_addc_u32 s57, s57, 0
	global_load_dwordx4 v[8:11], v168, s[56:57]
	s_add_u32 s56, s56, s48
	s_addc_u32 s57, s57, 0
	global_load_dwordx4 v[12:15], v168, s[56:57]
	s_add_u32 s56, s56, s48
	s_addc_u32 s57, s57, 0
	global_load_dwordx4 v[16:19], v168, s[56:57]
	s_add_u32 s56, s56, s48
	s_addc_u32 s57, s57, 0
	global_load_dwordx4 v[20:23], v168, s[56:57]
	s_add_u32 s56, s56, s48
	s_addc_u32 s57, s57, 0
	global_load_dwordx4 v[24:27], v168, s[56:57]
	s_add_u32 s56, s56, s48
	s_addc_u32 s57, s57, 0
	global_load_dwordx4 v[28:31], v168, s[56:57]
	s_add_u32 s56, s56, s48
	s_addc_u32 s57, s57, 0
	global_load_dwordx4 v[32:35], v168, s[56:57]
	s_add_u32 s56, s56, s48
	s_addc_u32 s57, s57, 0
	global_load_dwordx4 v[36:39], v168, s[56:57]
	s_add_u32 s56, s56, s48
	s_addc_u32 s57, s57, 0
	global_load_dwordx4 v[40:43], v168, s[56:57]
	s_add_u32 s56, s56, s48
	s_addc_u32 s57, s57, 0
	global_load_dwordx4 v[44:47], v168, s[56:57]
	s_add_u32 s56, s56, s48
	s_addc_u32 s57, s57, 0
	global_load_dwordx4 v[48:51], v168, s[56:57]
	s_add_u32 s56, s56, s48
	s_addc_u32 s57, s57, 0
	global_load_dwordx4 v[52:55], v168, s[56:57]
	s_add_u32 s56, s56, s48
	s_addc_u32 s57, s57, 0
	global_load_dwordx4 v[56:59], v168, s[56:57]
	s_add_u32 s56, s56, s48
	s_addc_u32 s57, s57, 0
	global_load_dwordx4 v[60:63], v168, s[56:57]
	s_mov_b32 s58, 1
cvt_nlA:
	ds_read2_b32 v[128:129], v166 offset0:0 offset1:65
	ds_read2_b32 v[130:131], v166 offset0:130 offset1:195
	ds_read2_b32 v[132:133], v167 offset0:0 offset1:65
	ds_read2_b32 v[134:135], v167 offset0:130 offset1:195
	ds_read2_b32 v[136:137], v166 offset0:8 offset1:73
	ds_read2_b32 v[138:139], v166 offset0:138 offset1:203
	ds_read2_b32 v[140:141], v167 offset0:8 offset1:73
	ds_read2_b32 v[142:143], v167 offset0:138 offset1:203
	s_waitcnt lgkmcnt(4)
	v_cvt_pk_bf16_f32 v152, v128, v129
	v_cvt_pk_bf16_f32 v153, v130, v131
	v_cvt_pk_bf16_f32 v154, v132, v133
	v_cvt_pk_bf16_f32 v155, v134, v135
	global_store_dwordx4 v169, v[152:155], s[54:55]
	s_add_u32 s54, s54, s49
	s_addc_u32 s55, s55, 0
	ds_read2_b32 v[144:145], v166 offset0:16 offset1:81
	ds_read2_b32 v[146:147], v166 offset0:146 offset1:211
	ds_read2_b32 v[148:149], v167 offset0:16 offset1:81
	ds_read2_b32 v[150:151], v167 offset0:146 offset1:211
	s_waitcnt lgkmcnt(4)
	v_cvt_pk_bf16_f32 v156, v136, v137
	v_cvt_pk_bf16_f32 v157, v138, v139
	v_cvt_pk_bf16_f32 v158, v140, v141
	v_cvt_pk_bf16_f32 v159, v142, v143
	global_store_dwordx4 v169, v[156:159], s[54:55]
	s_add_u32 s54, s54, s49
	s_addc_u32 s55, s55, 0
	ds_read2_b32 v[128:129], v166 offset0:24 offset1:89
	ds_read2_b32 v[130:131], v166 offset0:154 offset1:219
	ds_read2_b32 v[132:133], v167 offset0:24 offset1:89
	ds_read2_b32 v[134:135], v167 offset0:154 offset1:219
	s_waitcnt lgkmcnt(4)
	v_cvt_pk_bf16_f32 v152, v144, v145
	v_cvt_pk_bf16_f32 v153, v146, v147
	v_cvt_pk_bf16_f32 v154, v148, v149
	v_cvt_pk_bf16_f32 v155, v150, v151
	global_store_dwordx4 v169, v[152:155], s[54:55]
	s_add_u32 s54, s54, s49
	s_addc_u32 s55, s55, 0
	ds_read2_b32 v[136:137], v166 offset0:32 offset1:97
	ds_read2_b32 v[138:139], v166 offset0:162 offset1:227
	ds_read2_b32 v[140:141], v167 offset0:32 offset1:97
	ds_read2_b32 v[142:143], v167 offset0:162 offset1:227
	s_waitcnt lgkmcnt(4)
; #define LAS __attribute__((address_space(3)))
; #define LDS_WAIT() asm volatile("s_waitcnt lgkmcnt(0)" ::: "memory")
; __device__ __forceinline__ unsigned pk2(float lo, float hi) { const f32x2c v = {lo, hi}; return __builtin_bit_cast(unsigned, __builtin_convertvector(v, bf16x2c)); }
; __device__ __forceinline__ void tr_to_lds(const f32x4 (&v)[16], LAS float* scr, int lane) {
;     const int r4 = lane >> 4, c4 = (lane & 15) * 4;
; #pragma unroll
;     for (int i = 0; i < 16; ++i) { LAS float* s = scr + (4 * i + r4) * 65 + c4; s[0] = v[i].x; s[1] = v[i].y; s[2] = v[i].z; s[3] = v[i].w; }
;     LDS_WAIT(); asm volatile("" ::: "memory");
; }
; __device__ __forceinline__ void tr_store(bf16* dst, int K, const LAS float* scr, int lane) {
;     const int c = lane & 7;
; #pragma unroll
;     for (int j = 0; j < 8; ++j) { const int n = (lane >> 3) + 8 * j; const LAS float* s = scr + (8 * c) * 65 + n;
;         v4u o; o.x = pk2(s[0], s[65]); o.y = pk2(s[130], s[195]); o.z = pk2(s[260], s[325]); o.w = pk2(s[390], s[455]);
;         *(v4u*)(dst + (size_t)n * K + 8 * c) = o; }
;     LDS_WAIT(); asm volatile("" ::: "memory");
	v_cvt_pk_bf16_f32 v156, v128, v129
	v_cvt_pk_bf16_f32 v157, v130, v131
	v_cvt_pk_bf16_f32 v158, v132, v133
	v_cvt_pk_bf16_f32 v159, v134, v135
	global_store_dwordx4 v169, v[156:159], s[54:55]
	s_add_u32 s54, s54, s49
	s_addc_u32 s55, s55, 0
	ds_read2_b32 v[144:145], v166 offset0:40 offset1:105
	ds_read2_b32 v[146:147], v166 offset0:170 offset1:235
	ds_read2_b32 v[148:149], v167 offset0:40 offset1:105
	ds_read2_b32 v[150:151], v167 offset0:170 offset1:235
	s_waitcnt lgkmcnt(4)
	v_cvt_pk_bf16_f32 v152, v136, v137
	v_cvt_pk_bf16_f32 v153, v138, v139
	v_cvt_pk_bf16_f32 v154, v140, v141
	v_cvt_pk_bf16_f32 v155, v142, v143
	global_store_dwordx4 v169, v[152:155], s[54:55]
	s_add_u32 s54, s54, s49
	s_addc_u32 s55, s55, 0
	ds_read2_b32 v[128:129], v166 offset0:48 offset1:113
	ds_read2_b32 v[130:131], v166 offset0:178 offset1:243
	ds_read2_b32 v[132:133], v167 offset0:48 offset1:113
	ds_read2_b32 v[134:135], v167 offset0:178 offset1:243
	s_waitcnt lgkmcnt(4)
	v_cvt_pk_bf16_f32 v156, v144, v145
	v_cvt_pk_bf16_f32 v157, v146, v147
	v_cvt_pk_bf16_f32 v158, v148, v149
	v_cvt_pk_bf16_f32 v159, v150, v151
	global_store_dwordx4 v169, v[156:159], s[54:55]
	s_add_u32 s54, s54, s49
	s_addc_u32 s55, s55, 0
	ds_read2_b32 v[136:137], v166 offset0:56 offset1:121
	ds_read2_b32 v[138:139], v166 offset0:186 offset1:251
	ds_read2_b32 v[140:141], v167 offset0:56 offset1:121
	ds_read2_b32 v[142:143], v167 offset0:186 offset1:251
	s_waitcnt lgkmcnt(4)
	v_cvt_pk_bf16_f32 v152, v128, v129
	v_cvt_pk_bf16_f32 v153, v130, v131
	v_cvt_pk_bf16_f32 v154, v132, v133
	v_cvt_pk_bf16_f32 v155, v134, v135
	global_store_dwordx4 v169, v[152:155], s[54:55]
	s_add_u32 s54, s54, s49
	s_addc_u32 s55, s55, 0
	s_waitcnt lgkmcnt(0)
	v_cvt_pk_bf16_f32 v156, v136, v137
	v_cvt_pk_bf16_f32 v157, v138, v139
	v_cvt_pk_bf16_f32 v158, v140, v141
	v_cvt_pk_bf16_f32 v159, v142, v143
	global_store_dwordx4 v169, v[156:159], s[54:55]
	s_cmp_lg_u32 s59, 0
	s_cbranch_scc0 cvt_done
cvt_stepB:
	s_cmp_lg_u32 s58, 0
	s_cbranch_scc0 cvt_w0B
	s_waitcnt vmcnt(32)
	s_branch cvt_goB
cvt_w0B:
	s_waitcnt vmcnt(0)
cvt_goB:
	ds_write_b32 v163, v64 offset:0
	ds_write_b32 v163, v65 offset:4
	ds_write_b32 v163, v66 offset:8
	ds_write_b32 v163, v67 offset:12
	ds_write_b32 v163, v68 offset:1040
	ds_write_b32 v163, v69 offset:1044
	ds_write_b32 v163, v70 offset:1048
	ds_write_b32 v163, v71 offset:1052
	ds_write_b32 v163, v72 offset:2080
	ds_write_b32 v163, v73 offset:2084
	ds_write_b32 v163, v74 offset:2088
	ds_write_b32 v163, v75 offset:2092
	ds_write_b32 v163, v76 offset:3120
	ds_write_b32 v163, v77 offset:3124
	ds_write_b32 v163, v78 offset:3128
	ds_write_b32 v163, v79 offset:3132
	ds_write_b32 v163, v80 offset:4160
	ds_write_b32 v163, v81 offset:4164
	ds_write_b32 v163, v82 offset:4168
	ds_write_b32 v163, v83 offset:4172
	ds_write_b32 v163, v84 offset:5200
	ds_write_b32 v163, v85 offset:5204
	ds_write_b32 v163, v86 offset:5208
	ds_write_b32 v163, v87 offset:5212
	ds_write_b32 v163, v88 offset:6240
	ds_write_b32 v163, v89 offset:6244
	ds_write_b32 v163, v90 offset:6248
	ds_write_b32 v163, v91 offset:6252
	ds_write_b32 v163, v92 offset:7280
	ds_write_b32 v163, v93 offset:7284
	ds_write_b32 v163, v94 offset:7288
	ds_write_b32 v163, v95 offset:7292
	ds_write_b32 v163, v96 offset:8320
	ds_write_b32 v163, v97 offset:8324
	ds_write_b32 v163, v98 offset:8328
	ds_write_b32 v163, v99 offset:8332
	ds_write_b32 v163, v100 offset:9360
	ds_write_b32 v163, v101 offset:9364
	ds_write_b32 v163, v102 offset:9368
	ds_write_b32 v163, v103 offset:9372
	ds_write_b32 v163, v104 offset:10400
	ds_write_b32 v163, v105 offset:10404
	ds_write_b32 v163, v106 offset:10408
	ds_write_b32 v163, v107 offset:10412
	ds_write_b32 v163, v108 offset:11440
	ds_write_b32 v163, v109 offset:11444
	ds_write_b32 v163, v110 offset:11448
	ds_write_b32 v163, v111 offset:11452
	ds_write_b32 v163, v112 offset:12480
	ds_write_b32 v163, v113 offset:12484
	ds_write_b32 v163, v114 offset:12488
	ds_write_b32 v163, v115 offset:12492
	ds_write_b32 v163, v116 offset:13520
	ds_write_b32 v163, v117 offset:13524
	ds_write_b32 v163, v118 offset:13528
	ds_write_b32 v163, v119 offset:13532
	ds_write_b32 v163, v120 offset:14560
	ds_write_b32 v163, v121 offset:14564
	ds_write_b32 v163, v122 offset:14568
	ds_write_b32 v163, v123 offset:14572
	ds_write_b32 v163, v124 offset:15600
	ds_write_b32 v163, v125 offset:15604
	ds_write_b32 v163, v126 offset:15608
	ds_write_b32 v163, v127 offset:15612
	s_waitcnt lgkmcnt(0)
	s_mov_b32 s54, s78
	s_mov_b32 s55, s79
	s_lshl_b32 s49, s77, 4
	v_mul_lo_u32 v169, v165, s77
	v_lshl_add_u32 v169, v164, 3, v169
	v_lshlrev_b32_e32 v169, 1, v169
	s_mov_b32 s59, 0
cvt_nx8:
	s_cmp_lt_u32 s50, s23
	s_cbranch_scc1 cvt_nf8
	s_sub_i32 s50, s50, s23
	s_mov_b32 s23, 0
	s_add_i32 s70, s70, 1
	s_cmp_ge_i32 s70, s61
	s_cbranch_scc1 cvt_nlB
	s_mul_i32 s4, s70, 40
	s_getpc_b64 s[6:7]
	s_add_u32 s6, s6, __const._Z6seg_ati.segs@rel32@lo+4
	s_addc_u32 s7, s7, __const._Z6seg_ati.segs@rel32@hi+12
	s_add_u32 s6, s6, s4
	s_addc_u32 s7, s7, 0
	s_load_dwordx8 s[8:15], s[6:7], 0x0
	s_load_dwordx2 s[18:19], s[6:7], 0x20
	s_waitcnt lgkmcnt(0)
	s_lshr_b32 s20, s13, 6
	s_lshr_b32 s21, s11, 6
	s_mul_i32 s22, s20, s21
	s_lshl_b32 s4, s8, 3
	s_load_dwordx2 s[24:25], s[0:1], s4
	s_mul_i32 s5, s11, s10
	s_mul_i32 s5, s5, s9
	s_lshl_b32 s5, s5, 2
	s_lshl_b32 s6, s12, 2
	s_add_u32 s5, s5, s6
	s_waitcnt lgkmcnt(0)
	s_add_u32 s24, s24, s5
	s_addc_u32 s25, s25, 0
	s_mul_i32 s5, s14, 0x1a400000
	s_lshl_b32 s6, s15, 20
	s_add_u32 s5, s5, s6
	s_add_u32 s5, s5, 0x2d400000
	s_add_u32 s26, s68, s5
	s_addc_u32 s27, s69, 0
	s_sub_i32 s41, s22, 4096
	s_movk_i32 s23, 4096
	v_mul_lo_u32 v168, v161, s10
	v_add_u32_e32 v168, v168, v162
	v_lshlrev_b32_e32 v168, 2, v168
	s_lshl_b32 s48, s10, 4
	s_branch cvt_nx8
; __device__ __forceinline__ void tr_load(const float* src, int N, f32x4 (&v)[16], int lane) {
;     const int r4 = lane >> 4, c4 = (lane & 15) * 4;
; #pragma unroll
;     for (int i = 0; i < 16; ++i) v[i] = *(const f32x4*)(src + (size_t)(4 * i + r4) * N + c4);
; __device__ __forceinline__ void convert_segments(const Args& args, unsigned char* ws, LAS unsigned char* lds, int seg_lo, int seg_hi, int part_lo, int part_hi, int nparts, int wid, int nw, int wave, int lane) {
;     ...
;         if (it < it_hi) { const int kb = it / nblk, nb = it - kb * nblk; tr_load(W + (size_t)(64 * kb) * sg.N + sg.scol + 64 * nb, sg.N, v, lane); }
; #pragma unroll 1
;         for (; it < it_hi; it += nw) {
;             const int kb = it / nblk, nb = it - kb * nblk;
;             const int drow = sg.ilv ? (256 * (nb >> 1) + 64 * (nb & 1) + sg.drow) : (sg.drow + 64 * nb);
;             tr_to_lds(v, scr, lane);
;             const int itn = it + nw;
;             if (itn < it_hi) { const int kbn = itn / nblk, nbn = itn - kbn * nblk; tr_load(W + (size_t)(64 * kbn) * sg.N + sg.scol + 64 * nbn, sg.N, v, lane); }
cvt_nf8:
	s_add_i32 s43, s41, s50
	s_add_i32 s50, s50, s63
	v_cvt_f32_u32_e32 v170, s43
	v_cvt_f32_u32_e32 v171, s20
	v_rcp_f32_e32 v171, v171
	s_nop 1
	v_mul_f32_e32 v170, v170, v171
	v_cvt_u32_f32_e32 v170, v170
	s_nop 1
	v_readfirstlane_b32 s46, v170
	s_mul_i32 s72, s46, s20
	s_sub_i32 s47, s43, s72
	s_cmp_lt_i32 s47, 0
	s_cselect_b32 s72, s20, 0
	s_cselect_b32 s73, 1, 0
	s_add_i32 s47, s47, s72
	s_sub_i32 s46, s46, s73
	s_cmp_ge_i32 s47, s20
	s_cselect_b32 s72, s20, 0
	s_cselect_b32 s73, 1, 0
	s_sub_i32 s47, s47, s72
	s_add_i32 s46, s46, s73
	s_cmp_ge_i32 s47, s20
	s_cselect_b32 s72, s20, 0
	s_cselect_b32 s73, 1, 0
	s_sub_i32 s47, s47, s72
	s_add_i32 s46, s46, s73
	s_mul_i32 s4, s46, s10
	s_add_i32 s4, s4, s47
	s_lshl_b32 s4, s4, 8
	s_add_u32 s56, s24, s4
	s_addc_u32 s57, s25, 0
	s_lshr_b32 s4, s47, 1
	s_lshl_b32 s4, s4, 8
	s_and_b32 s5, s47, 1
	s_lshl_b32 s5, s5, 6
	s_add_i32 s4, s4, s5
	s_lshl_b32 s5, s47, 6
	s_cmp_lg_u32 s19, 0
	s_cselect_b32 s4, s4, s5
	s_add_i32 s4, s4, s18
	s_mul_i32 s4, s4, s11
	s_lshl_b32 s5, s46, 6
	s_add_i32 s4, s4, s5
	s_lshl_b32 s4, s4, 1
	s_add_u32 s78, s26, s4
	s_addc_u32 s79, s27, 0
	s_mov_b32 s77, s11
	global_load_dwordx4 v[64:67], v168, s[56:57]
	s_add_u32 s56, s56, s48
	s_addc_u32 s57, s57, 0
	global_load_dwordx4 v[68:71], v168, s[56:57]
	s_add_u32 s56, s56, s48
	s_addc_u32 s57, s57, 0
	global_load_dwordx4 v[72:75], v168, s[56:57]
	s_add_u32 s56, s56, s48
	s_addc_u32 s57, s57, 0
	global_load_dwordx4 v[76:79], v168, s[56:57]
	s_add_u32 s56, s56, s48
	s_addc_u32 s57, s57, 0
	global_load_dwordx4 v[80:83], v168, s[56:57]
	s_add_u32 s56, s56, s48
	s_addc_u32 s57, s57, 0
	global_load_dwordx4 v[84:87], v168, s[56:57]
	s_add_u32 s56, s56, s48
	s_addc_u32 s57, s57, 0
	global_load_dwordx4 v[88:91], v168, s[56:57]
	s_add_u32 s56, s56, s48
	s_addc_u32 s57, s57, 0
	global_load_dwordx4 v[92:95], v168, s[56:57]
	s_add_u32 s56, s56, s48
	s_addc_u32 s57, s57, 0
	global_load_dwordx4 v[96:99], v168, s[56:57]
	s_add_u32 s56, s56, s48
	s_addc_u32 s57, s57, 0
	global_load_dwordx4 v[100:103], v168, s[56:57]
	s_add_u32 s56, s56, s48
	s_addc_u32 s57, s57, 0
	global_load_dwordx4 v[104:107], v168, s[56:57]
	s_add_u32 s56, s56, s48
	s_addc_u32 s57, s57, 0
	global_load_dwordx4 v[108:111], v168, s[56:57]
	s_add_u32 s56, s56, s48
	s_addc_u32 s57, s57, 0
	global_load_dwordx4 v[112:115], v168, s[56:57]
	s_add_u32 s56, s56, s48
	s_addc_u32 s57, s57, 0
	global_load_dwordx4 v[116:119], v168, s[56:57]
	s_add_u32 s56, s56, s48
	s_addc_u32 s57, s57, 0
	global_load_dwordx4 v[120:123], v168, s[56:57]
	s_add_u32 s56, s56, s48
	s_addc_u32 s57, s57, 0
	global_load_dwordx4 v[124:127], v168, s[56:57]
	s_mov_b32 s59, 1
; #define LAS __attribute__((address_space(3)))
; #define LDS_WAIT() asm volatile("s_waitcnt lgkmcnt(0)" ::: "memory")
; __device__ __forceinline__ unsigned pk2(float lo, float hi) { const f32x2c v = {lo, hi}; return __builtin_bit_cast(unsigned, __builtin_convertvector(v, bf16x2c)); }
; __device__ __forceinline__ unsigned xb_add(unsigned* p, unsigned v) { return __hip_atomic_fetch_add(p, v, __ATOMIC_RELAXED, __HIP_MEMORY_SCOPE_AGENT); }
; __device__ __forceinline__ void xcd_barrier(const XcdBarrier& b) {
;     asm volatile("s_waitcnt vmcnt(0)" ::: "memory");
;     __syncthreads();
;     if (threadIdx.x == 0) {
;         unsigned* bar = b.bar;
;         __builtin_amdgcn_s_waitcnt(0);
;         unsigned nloc = b.st[0], nx = b.st[1];
;         if (nloc == 0u) { xcd_barrier_complete(bar, b.x, nloc, nx); b.st[0] = nloc; b.st[1] = nx; }
;         const unsigned old = xb_add(&bar[XB_XSUB(b.x)], 1u);
; __device__ __forceinline__ void tr_store(bf16* dst, int K, const LAS float* scr, int lane) {
;     const int c = lane & 7;
; #pragma unroll
;     for (int j = 0; j < 8; ++j) { const int n = (lane >> 3) + 8 * j; const LAS float* s = scr + (8 * c) * 65 + n;
;         v4u o; o.x = pk2(s[0], s[65]); o.y = pk2(s[130], s[195]); o.z = pk2(s[260], s[325]); o.w = pk2(s[390], s[455]);
;         *(v4u*)(dst + (size_t)n * K + 8 * c) = o; }
;     LDS_WAIT(); asm volatile("" ::: "memory");
cvt_nlB:
	ds_read2_b32 v[128:129], v166 offset0:0 offset1:65
	ds_read2_b32 v[130:131], v166 offset0:130 offset1:195
	ds_read2_b32 v[132:133], v167 offset0:0 offset1:65
	ds_read2_b32 v[134:135], v167 offset0:130 offset1:195
	ds_read2_b32 v[136:137], v166 offset0:8 offset1:73
	ds_read2_b32 v[138:139], v166 offset0:138 offset1:203
	ds_read2_b32 v[140:141], v167 offset0:8 offset1:73
	ds_read2_b32 v[142:143], v167 offset0:138 offset1:203
	s_waitcnt lgkmcnt(4)
	v_cvt_pk_bf16_f32 v152, v128, v129
	v_cvt_pk_bf16_f32 v153, v130, v131
	v_cvt_pk_bf16_f32 v154, v132, v133
	v_cvt_pk_bf16_f32 v155, v134, v135
	global_store_dwordx4 v169, v[152:155], s[54:55]
	s_add_u32 s54, s54, s49
	s_addc_u32 s55, s55, 0
	ds_read2_b32 v[144:145], v166 offset0:16 offset1:81
	ds_read2_b32 v[146:147], v166 offset0:146 offset1:211
	ds_read2_b32 v[148:149], v167 offset0:16 offset1:81
	ds_read2_b32 v[150:151], v167 offset0:146 offset1:211
	s_waitcnt lgkmcnt(4)
	v_cvt_pk_bf16_f32 v156, v136, v137
	v_cvt_pk_bf16_f32 v157, v138, v139
	v_cvt_pk_bf16_f32 v158, v140, v141
	v_cvt_pk_bf16_f32 v159, v142, v143
	global_store_dwordx4 v169, v[156:159], s[54:55]
	s_add_u32 s54, s54, s49
	s_addc_u32 s55, s55, 0
	ds_read2_b32 v[128:129], v166 offset0:24 offset1:89
	ds_read2_b32 v[130:131], v166 offset0:154 offset1:219
	ds_read2_b32 v[132:133], v167 offset0:24 offset1:89
	ds_read2_b32 v[134:135], v167 offset0:154 offset1:219
	s_waitcnt lgkmcnt(4)
	v_cvt_pk_bf16_f32 v152, v144, v145
	v_cvt_pk_bf16_f32 v153, v146, v147
	v_cvt_pk_bf16_f32 v154, v148, v149
	v_cvt_pk_bf16_f32 v155, v150, v151
	global_store_dwordx4 v169, v[152:155], s[54:55]
	s_add_u32 s54, s54, s49
	s_addc_u32 s55, s55, 0
	ds_read2_b32 v[136:137], v166 offset0:32 offset1:97
	ds_read2_b32 v[138:139], v166 offset0:162 offset1:227
	ds_read2_b32 v[140:141], v167 offset0:32 offset1:97
	ds_read2_b32 v[142:143], v167 offset0:162 offset1:227
	s_waitcnt lgkmcnt(4)
	v_cvt_pk_bf16_f32 v156, v128, v129
	v_cvt_pk_bf16_f32 v157, v130, v131
	v_cvt_pk_bf16_f32 v158, v132, v133
	v_cvt_pk_bf16_f32 v159, v134, v135
	global_store_dwordx4 v169, v[156:159], s[54:55]
	s_add_u32 s54, s54, s49
	s_addc_u32 s55, s55, 0
	ds_read2_b32 v[144:145], v166 offset0:40 offset1:105
	ds_read2_b32 v[146:147], v166 offset0:170 offset1:235
	ds_read2_b32 v[148:149], v167 offset0:40 offset1:105
	ds_read2_b32 v[150:151], v167 offset0:170 offset1:235
	s_waitcnt lgkmcnt(4)
	v_cvt_pk_bf16_f32 v152, v136, v137
	v_cvt_pk_bf16_f32 v153, v138, v139
	v_cvt_pk_bf16_f32 v154, v140, v141
	v_cvt_pk_bf16_f32 v155, v142, v143
	global_store_dwordx4 v169, v[152:155], s[54:55]
	s_add_u32 s54, s54, s49
	s_addc_u32 s55, s55, 0
	ds_read2_b32 v[128:129], v166 offset0:48 offset1:113
	ds_read2_b32 v[130:131], v166 offset0:178 offset1:243
	ds_read2_b32 v[132:133], v167 offset0:48 offset1:113
	ds_read2_b32 v[134:135], v167 offset0:178 offset1:243
	s_waitcnt lgkmcnt(4)
	v_cvt_pk_bf16_f32 v156, v144, v145
	v_cvt_pk_bf16_f32 v157, v146, v147
	v_cvt_pk_bf16_f32 v158, v148, v149
	v_cvt_pk_bf16_f32 v159, v150, v151
	global_store_dwordx4 v169, v[156:159], s[54:55]
	s_add_u32 s54, s54, s49
	s_addc_u32 s55, s55, 0
	ds_read2_b32 v[136:137], v166 offset0:56 offset1:121
	ds_read2_b32 v[138:139], v166 offset0:186 offset1:251
	ds_read2_b32 v[140:141], v167 offset0:56 offset1:121
	ds_read2_b32 v[142:143], v167 offset0:186 offset1:251
	s_waitcnt lgkmcnt(4)
	v_cvt_pk_bf16_f32 v152, v128, v129
	v_cvt_pk_bf16_f32 v153, v130, v131
	v_cvt_pk_bf16_f32 v154, v132, v133
	v_cvt_pk_bf16_f32 v155, v134, v135
	global_store_dwordx4 v169, v[152:155], s[54:55]
	s_add_u32 s54, s54, s49
	s_addc_u32 s55, s55, 0
	s_waitcnt lgkmcnt(0)
	v_cvt_pk_bf16_f32 v156, v136, v137
	v_cvt_pk_bf16_f32 v157, v138, v139
	v_cvt_pk_bf16_f32 v158, v140, v141
	v_cvt_pk_bf16_f32 v159, v142, v143
	global_store_dwordx4 v169, v[156:159], s[54:55]
	s_cmp_lg_u32 s58, 0
	s_cbranch_scc0 cvt_done
	s_branch cvt_stepA
cvt_done:
	s_waitcnt vmcnt(0) lgkmcnt(0)
	s_cmp_gt_i32 s37, 12
	s_cselect_b64 s[4:5], -1, 0
	s_cmp_lt_i32 s37, 13
	s_cbranch_scc1 .LBB0_1459
	s_waitcnt vmcnt(0)
	s_waitcnt vmcnt(0) lgkmcnt(0)
	s_barrier
	s_and_saveexec_b64 s[6:7], s[16:17]
	s_cbranch_execz .LBB0_1458
	s_add_i32 s8, 0, 0x23160
	v_mov_b32_e32 v0, s8
	s_waitcnt vmcnt(0) expcnt(0) lgkmcnt(0)
	ds_read_b32 v2, v0
	s_add_i32 s8, 0, 0x23164
	v_mov_b32_e32 v0, s8
	ds_read_b32 v0, v0
	s_waitcnt lgkmcnt(1)
	v_cmp_ne_u32_e32 vcc, 0, v2
	s_cbranch_vccnz .LBB0_1422
	s_load_dwordx2 s[12:13], s[34:35], 0x4
	s_add_u32 s8, s28, 0x4200
	s_addc_u32 s9, s29, 0
	s_add_u32 s10, s28, 0x4400
	s_addc_u32 s11, s29, 0
	s_waitcnt lgkmcnt(0)
	s_mul_i32 s39, s12, s88
	s_add_u32 s12, s28, 0x4500
	s_mul_i32 s39, s39, s13
	s_addc_u32 s13, s29, 0
	s_add_u32 s14, s28, 0x4600
	s_addc_u32 s15, s29, 0
	s_add_u32 s18, s28, 0x4700
	s_addc_u32 s19, s29, 0
	s_add_u32 s20, s28, 0x4800
	s_addc_u32 s21, s29, 0
	s_add_u32 s22, s28, 0x4900
	s_addc_u32 s23, s29, 0
	s_add_u32 s24, s28, 0x4a00
	s_addc_u32 s25, s29, 0
	s_add_u32 s26, s28, 0x4b00
	s_addc_u32 s27, s29, 0
	s_add_u32 s42, s28, 0x4c00
	s_addc_u32 s43, s29, 0
	s_add_u32 s44, s28, 0x4d00
	s_addc_u32 s45, s29, 0
	s_add_u32 s46, s28, 0x4e00
	s_addc_u32 s47, s29, 0
	s_add_u32 s48, s28, 0x4f00
	s_addc_u32 s49, s29, 0
	s_add_u32 s50, s28, 0x5000
	s_addc_u32 s51, s29, 0
	s_add_u32 s52, s28, 0x5100
	s_addc_u32 s53, s29, 0
	s_add_u32 s54, s28, 0x5200
	s_addc_u32 s55, s29, 0
	s_add_u32 s56, s28, 0x5300
	s_addc_u32 s57, s29, 0
	s_mov_b32 s41, 1
	v_mov_b32_e32 v16, 0
	s_branch .LBB0_1410
